# GEMM_in main loop: last 4 MFMAs of an iteration carried across the loop-back barrier and issued between the next iteration's LDS-DMA groups (operands already in v236-v255)
# speedup vs baseline: 1.0322x; 1.0069x over previous
; DI void gemm_tile(const Params& p, const GemmJob& j, int mt, int nt, char* smem) {
;     ...
;   const int t0 = mt * 256, n0 = nt * 128;
;   const int rl = lane >> 2, c8s = ((lane & 3) ^ ((lane >> 4) & 3)) * 8;
;   const int nk = j.K >> 5;
;   f32x16 acc[2][4];
; #pragma unroll
;   for (int a = 0; a < 2; ++a)
; #pragma unroll
;     for (int b = 0; b < 4; ++b)
; #pragma unroll
;       for (int i = 0; i < 16; ++i) acc[a][b][i] = 0.f;
;   auto glds = [&](int kt, int stage) {
;     char* sb = smem + stage * GSTAGE;
;     const unsigned ko = j.amode ? (unsigned)((kt >> 1) * j.lda + (kt & 1) * 32) : (unsigned)(kt * 32);
; #pragma unroll
;     for (int q = 0; q < 2; ++q) {
;       const int ch = q * 4 + wid;
;       const bf16_t* src = j.bblk ? j.Bt + ((size_t)kt * j.bblk + n0 + 16 * ch + rl) * 32 + c8s : j.Bt + (size_t)(n0 + 16 * ch + rl) * j.K + kt * 32 + c8s;
;       __builtin_amdgcn_global_load_lds((gptr_t)src, (lptr_t)(sb + ch * 1024), 16, 0, 0);
;     }
; #pragma unroll
;     for (int q = 0; q < 4; ++q) {
;       const int ch = q * 4 + wid;
;       const bf16_t* src = j.ablk ? j.A + ((size_t)kt * j.ablk + t0 + 16 * ch + rl) * 32 + c8s : j.A + a_rowoff(j, t0 + 16 * ch + rl) + ko + c8s;
;       __builtin_amdgcn_global_load_lds((gptr_t)src, (lptr_t)(sb + 8192 + ch * 1024), 16, 0, 0);
;     }
;   };
;   const int fr = (r >> 2) & 3; const int o0 = (h ^ fr) * 16;
;   __syncthreads();
;   glds(0, 0);
;   if (nk > 1) glds(1, 1);
.LBB0_102:
	v_lshl_add_u64 v[6:7], v[6:7], 0, v[0:1]
	s_add_i32 m0, s95, 0x6000
	v_readlane_b32 s12, v229, 29
	global_load_lds_dwordx4 v[6:7], off
	v_or_b32_e32 v7, s11, v3
	v_or_b32_e32 v6, s10, v2
	v_lshl_add_u64 v[10:11], v[6:7], 0, s[8:9]
	v_lshlrev_b64 v[10:11], 6, v[10:11]
	v_readlane_b32 s22, v229, 39
	v_readlane_b32 s23, v229, 40
	s_add_i32 m0, s94, 0x8000
	v_and_b32_e32 v144, 31, v145
	v_lshl_add_u64 v[10:11], s[22:23], 0, v[10:11]
	v_lshl_add_u64 v[10:11], v[10:11], 0, v[0:1]
	v_lshl_add_u64 v[10:11], v[10:11], 0, s[88:89]
	global_load_lds_dwordx4 v[10:11], off
	v_lshl_add_u64 v[10:11], v[6:7], 0, v[4:5]
	v_lshlrev_b64 v[10:11], 6, v[10:11]
	v_lshl_add_u64 v[10:11], s[22:23], 0, v[10:11]
	v_lshl_add_u64 v[10:11], v[10:11], 0, v[0:1]
	v_lshl_add_u64 v[10:11], v[10:11], 0, s[88:89]
	s_add_i32 m0, s95, 0x8000
	s_and_b32 s11, s72, 0x3ffff80
	global_load_lds_dwordx4 v[10:11], off
	v_lshl_add_u64 v[10:11], v[6:7], 0, s[62:63]
	v_lshlrev_b64 v[10:11], 6, v[10:11]
	v_lshl_add_u64 v[6:7], v[6:7], 0, s[66:67]
	v_lshl_add_u64 v[10:11], s[22:23], 0, v[10:11]
	v_lshlrev_b64 v[6:7], 6, v[6:7]
	v_lshl_add_u64 v[10:11], v[10:11], 0, v[0:1]
	v_lshl_add_u64 v[6:7], s[22:23], 0, v[6:7]
	v_lshl_add_u64 v[10:11], v[10:11], 0, s[88:89]
	s_add_i32 m0, s36, 0x8000
	v_lshl_add_u64 v[6:7], v[6:7], 0, v[0:1]
	global_load_lds_dwordx4 v[10:11], off
	v_lshl_add_u64 v[6:7], v[6:7], 0, s[88:89]
	s_add_i32 m0, s37, 0x8000
	s_and_b32 s38, s28, 3
	global_load_lds_dwordx4 v[6:7], off
	v_or_b32_e32 v7, s87, v3
	v_or_b32_e32 v6, s86, v2
	v_lshl_add_u64 v[130:131], v[6:7], 0, s[8:9]
	v_lshl_add_u64 v[132:133], v[6:7], 0, v[4:5]
	v_or_b32_e32 v6, s11, v144
	s_mul_i32 s11, s83, s75
	s_sub_i32 s11, s29, s11
	s_and_b32 s11, s11, 0xffffff80
	s_add_i32 s11, s8, s11
	v_lshlrev_b32_e32 v148, 6, v6
	v_add_u32_e32 v6, s11, v2
	s_lshl_b32 s11, s73, 5
	s_and_b32 s54, s81, 1
	v_lshlrev_b32_e32 v7, 6, v144
	s_add_i32 s11, s80, s11
	v_lshl_or_b32 v149, s54, 12, v7
	v_ashrrev_i32_e32 v7, 31, v6
	s_add_i32 s11, s11, s38
	v_lshlrev_b64 v[10:11], 11, v[6:7]
	v_add_u32_e32 v6, 64, v6
	s_lshl_b32 s11, s11, 8
	v_ashrrev_i32_e32 v7, 31, v6
	s_ashr_i32 s36, s11, 31
	v_and_b32_e32 v9, 63, v145
	v_lshlrev_b64 v[6:7], 11, v[6:7]
	v_or_b32_e32 v3, s36, v3
	v_or_b32_e32 v2, s11, v2
	v_lshrrev_b32_e32 v146, 5, v9
	v_lshrrev_b32_e32 v9, 2, v145
	v_lshl_add_u64 v[136:137], s[68:69], 0, v[6:7]
	v_lshl_add_u64 v[6:7], v[2:3], 0, s[8:9]
	v_lshlrev_b32_e32 v8, 4, v8
	v_lshl_add_u64 v[2:3], v[2:3], 0, v[4:5]
	v_bitop3_b32 v9, v146, v9, 3 bitop3:0x78
	v_lshlrev_b64 v[6:7], 6, v[6:7]
	v_and_b32_e32 v8, 48, v8
	v_lshlrev_b64 v[2:3], 6, v[2:3]
	v_readlane_b32 s8, v229, 8
	v_lshlrev_b32_e32 v147, 4, v9
	v_or_b32_e32 v6, v6, v8
	v_or_b32_e32 v2, v2, v8
	v_readlane_b32 s9, v229, 9
	v_mov_b32_e32 v114, 0
	s_mov_b32 s70, 2
	v_lshl_add_u64 v[134:135], s[68:69], 0, v[10:11]
	v_lshl_add_u64 v[138:139], s[22:23], 0, v[6:7]
	v_lshl_add_u64 v[140:141], s[8:9], 0, v[2:3]
	s_mov_b32 s11, 0
	s_mov_b64 s[8:9], 0
	s_mov_b32 s62, 0
	v_mov_b32_e32 v115, v114
	v_mov_b32_e32 v116, v114
	v_mov_b32_e32 v117, v114
	v_mov_b32_e32 v118, v114
	v_mov_b32_e32 v119, v114
	v_mov_b32_e32 v120, v114
	v_mov_b32_e32 v121, v114
	v_mov_b32_e32 v122, v114
	v_mov_b32_e32 v123, v114
	v_mov_b32_e32 v124, v114
	v_mov_b32_e32 v125, v114
	v_mov_b32_e32 v126, v114
	v_mov_b32_e32 v127, v114
	v_mov_b32_e32 v128, v114
	v_mov_b32_e32 v129, v114
	v_mov_b32_e32 v82, v114
	v_mov_b32_e32 v83, v114
	v_mov_b32_e32 v84, v114
	v_mov_b32_e32 v85, v114
	v_mov_b32_e32 v86, v114
	v_mov_b32_e32 v87, v114
	v_mov_b32_e32 v88, v114
	v_mov_b32_e32 v89, v114
	v_mov_b32_e32 v90, v114
	v_mov_b32_e32 v91, v114
	v_mov_b32_e32 v92, v114
	v_mov_b32_e32 v93, v114
	v_mov_b32_e32 v94, v114
	v_mov_b32_e32 v95, v114
	v_mov_b32_e32 v96, v114
	v_mov_b32_e32 v97, v114
	v_mov_b32_e32 v50, v114
	v_mov_b32_e32 v51, v114
	v_mov_b32_e32 v52, v114
	v_mov_b32_e32 v53, v114
	v_mov_b32_e32 v54, v114
	v_mov_b32_e32 v55, v114
	v_mov_b32_e32 v56, v114
	v_mov_b32_e32 v57, v114
	v_mov_b32_e32 v58, v114
	v_mov_b32_e32 v59, v114
	v_mov_b32_e32 v60, v114
	v_mov_b32_e32 v61, v114
	v_mov_b32_e32 v62, v114
	v_mov_b32_e32 v63, v114
	v_mov_b32_e32 v64, v114
	v_mov_b32_e32 v65, v114
	v_mov_b32_e32 v18, v114
	v_mov_b32_e32 v19, v114
	v_mov_b32_e32 v20, v114
	v_mov_b32_e32 v21, v114
	v_mov_b32_e32 v22, v114
	v_mov_b32_e32 v23, v114
	v_mov_b32_e32 v24, v114
	v_mov_b32_e32 v25, v114
	v_mov_b32_e32 v26, v114
	v_mov_b32_e32 v27, v114
	v_mov_b32_e32 v28, v114
	v_mov_b32_e32 v29, v114
	v_mov_b32_e32 v30, v114
	v_mov_b32_e32 v31, v114
	v_mov_b32_e32 v32, v114
	v_mov_b32_e32 v33, v114
	v_mov_b32_e32 v98, v114
	v_mov_b32_e32 v99, v114
	v_mov_b32_e32 v100, v114
	v_mov_b32_e32 v101, v114
	v_mov_b32_e32 v102, v114
	v_mov_b32_e32 v103, v114
	v_mov_b32_e32 v104, v114
	v_mov_b32_e32 v105, v114
	v_mov_b32_e32 v106, v114
	v_mov_b32_e32 v107, v114
	v_mov_b32_e32 v108, v114
; DI f32x16 mfma32(bf16x8 a, bf16x8 b, f32x16 c) { return __builtin_amdgcn_mfma_f32_32x32x16_bf16(a, b, c, 0, 0, 0); }
; #define RAW_BARRIER() do { asm volatile("s_waitcnt lgkmcnt(0)" ::: "memory"); __builtin_amdgcn_s_barrier(); } while (0)
; DI void gemm_tile(const Params& p, const GemmJob& j, int mt, int nt, char* smem) {
;     ...
;   f32x16 acc[2][4];
; #pragma unroll
;   for (int a = 0; a < 2; ++a)
; #pragma unroll
;     for (int b = 0; b < 4; ++b)
; #pragma unroll
;       for (int i = 0; i < 16; ++i) acc[a][b][i] = 0.f;
;     ...
;   for (int kt = 0; kt < nk; ++kt) {
;     if (kt + 1 < nk) asm volatile("s_waitcnt vmcnt(6)" ::: "memory"); else asm volatile("s_waitcnt vmcnt(0)" ::: "memory");
;     RAW_BARRIER();
;     if (kt + 2 < nk) glds(kt + 2, st2);
;     const char* sb = smem + st * GSTAGE;
; #pragma unroll
;     for (int ks = 0; ks < 2; ++ks) {
;       const int off = ks ? (o0 ^ 32) : o0;
;       bf16x8 wf[2], xf[4];
; #pragma unroll
;       for (int a = 0; a < 2; ++a) wf[a] = *(const bf16x8*)(sb + (64 * wn + 32 * a + r) * 64 + off);
; #pragma unroll
;       for (int b = 0; b < 4; ++b) xf[b] = *(const bf16x8*)(sb + 8192 + (128 * wt + 32 * b + r) * 64 + off);
; #pragma unroll
;       for (int a = 0; a < 2; ++a)
; #pragma unroll
;         for (int b = 0; b < 4; ++b) acc[a][b] = mfma32(wf[a], xf[b], acc[a][b]);
;     }
;     st = (st == 2) ? 0 : st + 1; st2 = (st2 == 2) ? 0 : st2 + 1;
	v_mov_b32_e32 v109, v114
	v_mov_b32_e32 v110, v114
	v_mov_b32_e32 v111, v114
	v_mov_b32_e32 v112, v114
	v_mov_b32_e32 v113, v114
	v_mov_b32_e32 v66, v114
	v_mov_b32_e32 v67, v114
	v_mov_b32_e32 v68, v114
	v_mov_b32_e32 v69, v114
	v_mov_b32_e32 v70, v114
	v_mov_b32_e32 v71, v114
	v_mov_b32_e32 v72, v114
	v_mov_b32_e32 v73, v114
	v_mov_b32_e32 v74, v114
	v_mov_b32_e32 v75, v114
	v_mov_b32_e32 v76, v114
	v_mov_b32_e32 v77, v114
	v_mov_b32_e32 v78, v114
	v_mov_b32_e32 v79, v114
	v_mov_b32_e32 v80, v114
	v_mov_b32_e32 v81, v114
	v_mov_b32_e32 v34, v114
	v_mov_b32_e32 v35, v114
	v_mov_b32_e32 v36, v114
	v_mov_b32_e32 v37, v114
	v_mov_b32_e32 v38, v114
	v_mov_b32_e32 v39, v114
	v_mov_b32_e32 v40, v114
	v_mov_b32_e32 v41, v114
	v_mov_b32_e32 v42, v114
	v_mov_b32_e32 v43, v114
	v_mov_b32_e32 v44, v114
	v_mov_b32_e32 v45, v114
	v_mov_b32_e32 v46, v114
	v_mov_b32_e32 v47, v114
	v_mov_b32_e32 v48, v114
	v_mov_b32_e32 v49, v114
	v_mov_b32_e32 v2, v114
	v_mov_b32_e32 v3, v114
	v_mov_b32_e32 v4, v114
	v_mov_b32_e32 v5, v114
	v_mov_b32_e32 v6, v114
	v_mov_b32_e32 v7, v114
	v_mov_b32_e32 v8, v114
	v_mov_b32_e32 v9, v114
	v_mov_b32_e32 v10, v114
	v_mov_b32_e32 v11, v114
	v_mov_b32_e32 v12, v114
	v_mov_b32_e32 v13, v114
	v_mov_b32_e32 v14, v114
	v_mov_b32_e32 v15, v114
	v_mov_b32_e32 v16, v114
	v_mov_b32_e32 v17, v114
	v_xor_b32_e32 v150, 32, v147
	v_readlane_b32 s13, v229, 30
	v_readlane_b32 s14, v229, 31
	v_readlane_b32 s15, v229, 32
	v_readlane_b32 s16, v229, 33
	v_readlane_b32 s17, v229, 34
	v_readlane_b32 s18, v229, 35
	v_readlane_b32 s19, v229, 36
	v_readlane_b32 s20, v229, 37
	v_readlane_b32 s21, v229, 38
	v_readlane_b32 s24, v229, 41
	v_readlane_b32 s25, v229, 42
	v_readlane_b32 s26, v229, 43
	v_readlane_b32 s27, v229, 44
	v_mov_b32_e32 v236, 0
	v_mov_b32_e32 v237, 0
	v_mov_b32_e32 v238, 0
	v_mov_b32_e32 v239, 0
	v_mov_b32_e32 v240, 0
	v_mov_b32_e32 v241, 0
	v_mov_b32_e32 v242, 0
	v_mov_b32_e32 v243, 0
	v_mov_b32_e32 v244, 0
	v_mov_b32_e32 v245, 0
	v_mov_b32_e32 v246, 0
	v_mov_b32_e32 v247, 0
	v_mov_b32_e32 v248, 0
	v_mov_b32_e32 v249, 0
	v_mov_b32_e32 v250, 0
	v_mov_b32_e32 v251, 0
	v_mov_b32_e32 v252, 0
	v_mov_b32_e32 v253, 0
	v_mov_b32_e32 v254, 0
	v_mov_b32_e32 v255, 0
	s_branch .LBB0_104
.LBB0_103:
	s_add_i32 s37, s63, s33
	v_lshl_add_u64 v[232:233], v[232:233], 0, v[0:1]
	s_mov_b32 m0, s37
	v_lshl_add_u64 v[134:135], v[134:135], 0, 64
	global_load_lds_dwordx4 v[232:233], off
	v_mfma_f32_32x32x16_bf16 v[98:113], v[236:239], v[240:243], v[98:113]
	v_lshl_add_u64 v[232:233], v[138:139], 0, s[8:9]
	v_lshl_add_u64 v[234:235], v[232:233], 0, s[92:93]
	s_add_i32 m0, s36, 0x2000
	s_add_i32 s36, s63, s55
	global_load_lds_dwordx4 v[234:235], off
	v_mfma_f32_32x32x16_bf16 v[66:81], v[236:239], v[244:247], v[66:81]
	v_lshl_add_u64 v[234:235], v[140:141], 0, s[8:9]
	s_add_i32 m0, s37, 0x2000
	v_lshl_add_u64 v[136:137], v[136:137], 0, 64
	global_load_lds_dwordx4 v[234:235], off
	v_mfma_f32_32x32x16_bf16 v[34:49], v[236:239], v[248:251], v[34:49]
	v_lshl_add_u64 v[234:235], v[232:233], 0, s[84:85]
	s_add_i32 m0, s36, 0x2000
	s_add_i32 s36, s63, s58
	global_load_lds_dwordx4 v[234:235], off
	v_mfma_f32_32x32x16_bf16 v[2:17], v[236:239], v[252:255], v[2:17]
	v_lshl_add_u64 v[232:233], v[232:233], 0, s[52:53]
	s_add_i32 m0, s36, 0x2000
	s_nop 0
	global_load_lds_dwordx4 v[232:233], off
	v_add_u32_e32 v234, s100, v150
	v_add_u32_e32 v235, v234, v149
	v_add_u32_e32 v234, v234, v148
	s_waitcnt lgkmcnt(0)
	v_mfma_f32_32x32x16_bf16 v[114:129], v[152:155], v[156:159], v[114:129]
	ds_read_b128 v[236:239], v143 offset:2048
	s_add_i32 s36, s11, 1
	s_cmp_lg_u32 s11, 2
	s_cselect_b32 s11, s36, 0
	s_add_i32 s36, s70, 1
	s_cmp_lg_u32 s70, 2
	s_cselect_b32 s70, s36, 0
	v_mfma_f32_32x32x16_bf16 v[82:97], v[152:155], v[160:163], v[82:97]
	ds_read_b128 v[240:243], v234 offset:8192
	s_add_u32 s8, s8, 0x200000
	s_addc_u32 s9, s9, 0
	s_add_i32 s62, s62, 1
	s_cmp_eq_u32 s8, 0x3c00000
	v_mfma_f32_32x32x16_bf16 v[50:65], v[152:155], v[180:183], v[50:65]
	ds_read_b128 v[244:247], v234 offset:10240
	v_mfma_f32_32x32x16_bf16 v[18:33], v[152:155], v[184:187], v[18:33]
	ds_read_b128 v[248:251], v234 offset:12288
	s_waitcnt lgkmcnt(3)
	v_mfma_f32_32x32x16_bf16 v[98:113], v[236:239], v[156:159], v[98:113]
	ds_read_b128 v[252:255], v234 offset:14336
	v_mfma_f32_32x32x16_bf16 v[66:81], v[236:239], v[160:163], v[66:81]
	ds_read_b128 v[152:155], v235
	v_mfma_f32_32x32x16_bf16 v[34:49], v[236:239], v[180:183], v[34:49]
	v_mfma_f32_32x32x16_bf16 v[2:17], v[236:239], v[184:187], v[2:17]
	ds_read_b128 v[236:239], v235 offset:2048
	s_waitcnt lgkmcnt(1)
	v_mfma_f32_32x32x16_bf16 v[114:129], v[152:155], v[240:243], v[114:129]
	v_mfma_f32_32x32x16_bf16 v[82:97], v[152:155], v[244:247], v[82:97]
	v_mfma_f32_32x32x16_bf16 v[50:65], v[152:155], v[248:251], v[50:65]
	v_mfma_f32_32x32x16_bf16 v[18:33], v[152:155], v[252:255], v[18:33]
	s_cbranch_scc1 .LBB0_108

; DI f32x16 mfma32(bf16x8 a, bf16x8 b, f32x16 c) { return __builtin_amdgcn_mfma_f32_32x32x16_bf16(a, b, c, 0, 0, 0); }
; #define RAW_BARRIER() do { asm volatile("s_waitcnt lgkmcnt(0)" ::: "memory"); __builtin_amdgcn_s_barrier(); } while (0)
; DI void gemm_tile(const Params& p, const GemmJob& j, int mt, int nt, char* smem) {
;     ...
;   for (int kt = 0; kt < nk; ++kt) {
;     if (kt + 1 < nk) asm volatile("s_waitcnt vmcnt(6)" ::: "memory"); else asm volatile("s_waitcnt vmcnt(0)" ::: "memory");
;     RAW_BARRIER();
;     if (kt + 2 < nk) glds(kt + 2, st2);
;     const char* sb = smem + st * GSTAGE;
; #pragma unroll
;     for (int ks = 0; ks < 2; ++ks) {
;       const int off = ks ? (o0 ^ 32) : o0;
;       bf16x8 wf[2], xf[4];
; #pragma unroll
;       for (int a = 0; a < 2; ++a) wf[a] = *(const bf16x8*)(sb + (64 * wn + 32 * a + r) * 64 + off);
; #pragma unroll
;       for (int b = 0; b < 4; ++b) xf[b] = *(const bf16x8*)(sb + 8192 + (128 * wt + 32 * b + r) * 64 + off);
; #pragma unroll
;       for (int a = 0; a < 2; ++a)
; #pragma unroll
;         for (int b = 0; b < 4; ++b) acc[a][b] = mfma32(wf[a], xf[b], acc[a][b]);
;     }
;     st = (st == 2) ? 0 : st + 1; st2 = (st2 == 2) ? 0 : st2 + 1;
;   }
;   __syncthreads();
;   if (j.epi == E_SEG) {
;     const float* sp = p.ssqp + (size_t)(t0 + tid) * 8;
;     const f32x4 s0 = *(const f32x4*)sp, s1 = *(const f32x4*)(sp + 4);
;     rstd_s[tid] = rsqrtf(((s0[0] + s0[1]) + (s0[2] + s0[3]) + (s1[0] + s1[1]) + (s1[2] + s1[3])) * (1.f / 1024.f) + 1e-6f);
;     __syncthreads();
;   }
;   const int cb = n0 + 64 * wn;
;   if (j.epi == E_SEG) {
;     const Seg* sg = p.segs[j.layer]; const int nsg = p.nseg[j.layer];
;     {
;       int si = 0;
;       for (int q = 1; q < nsg; ++q) if (cb >= sg[q].nb) si = q;
.LBB0_108:
	s_waitcnt lgkmcnt(0)
	v_mfma_f32_32x32x16_bf16 v[98:113], v[236:239], v[240:243], v[98:113]
	v_mfma_f32_32x32x16_bf16 v[66:81], v[236:239], v[244:247], v[66:81]
	v_mfma_f32_32x32x16_bf16 v[34:49], v[236:239], v[248:251], v[34:49]
	v_mfma_f32_32x32x16_bf16 v[2:17], v[236:239], v[252:255], v[2:17]
	v_readlane_b32 s100, v229, 35
	v_readlane_b32 s101, v229, 36
	v_add_u32_e32 v244, s10, v145
	v_ashrrev_i32_e32 v245, 31, v244
	v_lshlrev_b64 v[244:245], 5, v[244:245]
	s_nop 0
	v_lshl_add_u64 v[244:245], s[100:101], 0, v[244:245]
	global_load_dwordx4 v[236:239], v[244:245], off offset:16
	global_load_dwordx4 v[240:243], v[244:245], off
	s_mul_i32 s6, s11, 0x6000
	s_add_i32 s7, s6, 0
	v_add_u32_e32 v0, s7, v147
	s_waitcnt vmcnt(8)
	v_add_u32_e32 v134, v0, v149
	v_add_u32_e32 v0, v0, v148
	s_waitcnt lgkmcnt(0)
	s_barrier
	ds_read_b128 v[130:133], v134
	ds_read_b128 v[134:137], v134 offset:2048
	ds_read_b128 v[138:141], v0 offset:8192
	ds_read_b128 v[152:155], v0 offset:10240
	ds_read_b128 v[156:159], v0 offset:12288
	ds_read_b128 v[160:163], v0 offset:14336
	s_waitcnt lgkmcnt(0)
	v_mfma_f32_32x32x16_bf16 v[114:129], v[130:133], v[138:141], v[114:129]
	v_add_u32_e32 v0, s7, v150
	s_addk_i32 s6, 0x6000
	s_cmp_lg_u32 s11, 2
	s_cselect_b32 s6, s6, 0
	s_add_i32 s6, s6, 0
	v_readlane_b32 s12, v229, 29
	v_readlane_b32 s18, v229, 35
	v_mfma_f32_32x32x16_bf16 v[82:97], v[130:133], v[152:155], v[82:97]
	v_readlane_b32 s19, v229, 36
	v_readlane_b32 s13, v229, 30
	v_readlane_b32 s14, v229, 31
	v_readlane_b32 s15, v229, 32
	v_readlane_b32 s16, v229, 33
	v_readlane_b32 s17, v229, 34
	v_readlane_b32 s20, v229, 37
	v_mfma_f32_32x32x16_bf16 v[50:65], v[130:133], v[156:159], v[50:65]
	v_readlane_b32 s21, v229, 38
	v_readlane_b32 s22, v229, 39
	v_readlane_b32 s23, v229, 40
	v_readlane_b32 s24, v229, 41
	v_readlane_b32 s25, v229, 42
	v_readlane_b32 s26, v229, 43
	v_readlane_b32 s27, v229, 44
	v_mfma_f32_32x32x16_bf16 v[18:33], v[130:133], v[160:163], v[18:33]
	v_mfma_f32_32x32x16_bf16 v[98:113], v[134:137], v[138:141], v[98:113]
	v_mfma_f32_32x32x16_bf16 v[66:81], v[134:137], v[152:155], v[66:81]
	v_mfma_f32_32x32x16_bf16 v[34:49], v[134:137], v[156:159], v[34:49]
	v_mfma_f32_32x32x16_bf16 v[2:17], v[134:137], v[160:163], v[2:17]
	v_add_u32_e32 v134, v0, v149
	v_add_u32_e32 v0, v0, v148
	ds_read_b128 v[130:133], v134
	ds_read_b128 v[134:137], v134 offset:2048
	ds_read_b128 v[138:141], v0 offset:8192
	ds_read_b128 v[152:155], v0 offset:10240
	ds_read_b128 v[156:159], v0 offset:12288
	ds_read_b128 v[160:163], v0 offset:14336
	v_add_u32_e32 v0, s6, v147
	s_waitcnt vmcnt(0)
	s_waitcnt lgkmcnt(0)
	s_waitcnt lgkmcnt(0)
	v_mfma_f32_32x32x16_bf16 v[114:129], v[130:133], v[138:141], v[114:129]
	s_barrier
	v_mfma_f32_32x32x16_bf16 v[82:97], v[130:133], v[152:155], v[82:97]
	v_mfma_f32_32x32x16_bf16 v[50:65], v[130:133], v[156:159], v[50:65]
	v_mfma_f32_32x32x16_bf16 v[18:33], v[130:133], v[160:163], v[18:33]
	v_mfma_f32_32x32x16_bf16 v[98:113], v[134:137], v[138:141], v[98:113]
	v_mfma_f32_32x32x16_bf16 v[66:81], v[134:137], v[152:155], v[66:81]
	v_mfma_f32_32x32x16_bf16 v[34:49], v[134:137], v[156:159], v[34:49]
	v_mfma_f32_32x32x16_bf16 v[2:17], v[134:137], v[160:163], v[2:17]
	v_add_u32_e32 v134, v0, v149
	v_add_u32_e32 v0, v0, v148
	ds_read_b128 v[130:133], v134
	ds_read_b128 v[134:137], v134 offset:2048
	ds_read_b128 v[138:141], v0 offset:8192
	ds_read_b128 v[152:155], v0 offset:10240
	ds_read_b128 v[156:159], v0 offset:12288
	ds_read_b128 v[160:163], v0 offset:14336
	v_add_u32_e32 v0, s6, v150
	s_mov_b32 s6, 0x800000
	s_waitcnt lgkmcnt(0)
	v_mfma_f32_32x32x16_bf16 v[114:129], v[130:133], v[138:141], v[114:129]
	v_mfma_f32_32x32x16_bf16 v[82:97], v[130:133], v[152:155], v[82:97]
	v_mfma_f32_32x32x16_bf16 v[50:65], v[130:133], v[156:159], v[50:65]
	v_mfma_f32_32x32x16_bf16 v[18:33], v[130:133], v[160:163], v[18:33]
	v_mfma_f32_32x32x16_bf16 v[98:113], v[134:137], v[138:141], v[98:113]
	v_mfma_f32_32x32x16_bf16 v[66:81], v[134:137], v[152:155], v[66:81]
	v_mfma_f32_32x32x16_bf16 v[34:49], v[134:137], v[156:159], v[34:49]
	v_mfma_f32_32x32x16_bf16 v[2:17], v[134:137], v[160:163], v[2:17]
	v_add_u32_e32 v134, v0, v149
	v_add_u32_e32 v0, v0, v148
	ds_read_b128 v[130:133], v134
	ds_read_b128 v[134:137], v134 offset:2048
	ds_read_b128 v[138:141], v0 offset:8192
	ds_read_b128 v[148:151], v0 offset:10240
	ds_read_b128 v[152:155], v0 offset:12288
	ds_read_b128 v[156:159], v0 offset:14336
	s_waitcnt vmcnt(0) lgkmcnt(0)
	s_barrier
	v_mfma_f32_32x32x16_bf16 v[114:129], v[130:133], v[138:141], v[114:129]
	v_mfma_f32_32x32x16_bf16 v[82:97], v[130:133], v[148:151], v[82:97]
	v_mfma_f32_32x32x16_bf16 v[50:65], v[130:133], v[152:155], v[50:65]
	v_mfma_f32_32x32x16_bf16 v[18:33], v[130:133], v[156:159], v[18:33]
	v_add_u32_e32 v130, s10, v145
	v_ashrrev_i32_e32 v131, 31, v130
	v_lshlrev_b64 v[130:131], 5, v[130:131]
	v_mfma_f32_32x32x16_bf16 v[98:113], v[134:137], v[138:141], v[98:113]
	v_mfma_f32_32x32x16_bf16 v[66:81], v[134:137], v[148:151], v[66:81]
	v_mfma_f32_32x32x16_bf16 v[34:49], v[134:137], v[152:155], v[34:49]
	v_mfma_f32_32x32x16_bf16 v[2:17], v[134:137], v[156:159], v[2:17]
	v_lshl_add_u64 v[134:135], s[18:19], 0, v[130:131]
	s_waitcnt vmcnt(0)
	v_mov_b32_e32 v130, v236
	v_mov_b32_e32 v131, v237
	v_mov_b32_e32 v132, v238
	v_mov_b32_e32 v133, v239
	v_mov_b32_e32 v134, v240
	v_mov_b32_e32 v135, v241
	v_mov_b32_e32 v136, v242
	v_mov_b32_e32 v137, v243
	v_mov_b32_e32 v138, v135
	v_mov_b32_e32 v139, v136
	v_mov_b32_e32 v135, v137
	v_pk_add_f32 v[134:135], v[138:139], v[134:135]
	v_mov_b32_e32 v136, v132
	v_mov_b32_e32 v137, v130
	v_mov_b32_e32 v130, v133
	v_pk_add_f32 v[130:131], v[136:137], v[130:131]
	v_add_f32_e32 v0, v134, v135
	v_add_f32_e32 v0, v0, v131
	v_add_f32_e32 v0, v130, v0
	v_fmamk_f32 v0, v0, 0x3a800000, v201
	v_cmp_gt_f32_e32 vcc, s6, v0
	v_mul_f32_e32 v130, 0x4b800000, v0
	s_lshl_b32 s6, s54, 6
	v_cndmask_b32_e32 v0, v0, v130, vcc
	v_rsq_f32_e32 v0, v0
	s_or_b32 s11, s6, s86
	s_mul_i32 s6, s50, 0xfffffe84
	s_add_u32 s6, s64, s6
	v_mul_f32_e32 v130, 0x45800000, v0
	v_cndmask_b32_e32 v0, v0, v130, vcc
	v_lshl_add_u32 v130, v145, 2, 0
	v_add_u32_e32 v130, 0x12000, v130
	s_addc_u32 s7, s65, s96
	ds_write_b32 v130, v0
	s_waitcnt lgkmcnt(0)
	s_barrier
	s_load_dword s31, s[6:7], 0x998
	s_mov_b64 s[6:7], 0
	s_waitcnt lgkmcnt(0)
	s_cmp_gt_i32 s31, 1
	s_cselect_b64 s[94:95], -1, 0
	s_cmp_lt_i32 s31, 2
	s_cbranch_scc1 .LBB0_121
	s_cmp_eq_u32 s31, 2
	s_cbranch_scc1 .LBB0_117
	s_add_i32 s8, s31, -1
	s_and_b32 s9, s8, -2
	s_mov_b32 s33, s11
	s_mov_b32 s6, 2
	s_mov_b32 s58, 1
	s_brev_b32 s36, 1
	s_mov_b32 s38, s9
	s_brev_b32 s37, 1
